# epilogue de-serialisation: the residual-GEMM epilogues (ffn_out x2, out, ple) issue the 4 x-row loads of a loop trip together with counted vmcnt instead of load-wait-store per row
# speedup vs baseline: 1.0060x; 1.0040x over previous
; DI unsigned pk2(float a, float b) { f32x2 v = {a, b}; bf16x2_t r = __builtin_convertvector(v, bf16x2_t); return __builtin_bit_cast(unsigned, r); }
; template <int NJ> DI void resid_epilogue(float* __restrict__ x, bf16_t* __restrict__ xb, float* __restrict__ ssn, int mt, int nt, const float* cl, float scale) {
;     ...
; #pragma unroll 4
;   for (int it = 0; it < NP; ++it) {
;     const int row = r0 + RPP * it;
;     const f32x4 c = *(const f32x4*)(cl + row * CLD + c4);
;     const size_t gi = (size_t)(mt * 128 + row) * DM + nt * (64 * NJ) + c4;
;     f32x4 xv = *(const f32x4*)(x + gi);
;     xv = xv + scale * c;
;     *(f32x4*)(x + gi) = xv;
;     u32x2 p; p.x = pk2(xv[0], xv[1]); p.y = pk2(xv[2], xv[3]);
;     *(u32x2*)(xb + (size_t)(mt * 128 + row) * LDX + nt * (64 * NJ) + c4) = p;
;     float s_ = xv[0] * xv[0] + xv[1] * xv[1] + xv[2] * xv[2] + xv[3] * xv[3];
;     if (NJ == 2) s_ += __shfl_xor(s_, 16);
;     s_ += __shfl_xor(s_, 8); s_ += __shfl_xor(s_, 4); s_ += __shfl_xor(s_, 2); s_ += __shfl_xor(s_, 1);
;     if ((tid & (LPR - 1)) == 0) atomicAdd(ssn + mt * 128 + row, s_);
;   }
.LBB0_429:
	v_lshl_add_u64 v[20:21], v[6:7], 0, s[0:1]
	s_waitcnt lgkmcnt(0)
	global_load_dwordx4 v[28:31], v[20:21], off
	v_lshl_add_u64 v[38:39], v[16:17], 0, s[0:1]
	global_load_dwordx4 v[44:47], v[38:39], off
	v_lshl_add_u64 v[40:41], v[10:11], 0, s[0:1]
	global_load_dwordx4 v[48:51], v[40:41], off
	v_lshl_add_u64 v[42:43], v[4:5], 0, s[0:1]
	global_load_dwordx4 v[52:55], v[42:43], off
	ds_read_b128 v[32:35], v27
	s_waitcnt vmcnt(3) lgkmcnt(0)
	v_pk_fma_f32 v[28:29], v[32:33], 0.5, v[28:29] op_sel_hi:[1,0,1]
	s_nop 0
	v_mul_f32_e32 v0, v29, v29
	v_pk_fma_f32 v[30:31], v[34:35], 0.5, v[30:31] op_sel_hi:[1,0,1]
	v_fmac_f32_e32 v0, v28, v28
	v_fmac_f32_e32 v0, v30, v30
	v_fmac_f32_e32 v0, v31, v31
	ds_bpermute_b32 v32, v22, v0
	global_store_dwordx4 v[20:21], v[28:31], off
	v_cvt_pk_bf16_f32 v20, v28, v29
	v_cvt_pk_bf16_f32 v21, v30, v31
	v_lshl_add_u64 v[30:31], s[94:95], 0, v[18:19]
	s_waitcnt lgkmcnt(0)
	v_add_f32_e32 v0, v0, v32
	ds_bpermute_b32 v32, v23, v0
	global_store_dwordx2 v[30:31], v[20:21], off
	v_lshl_add_u64 v[20:21], s[94:95], 0, v[12:13]
	s_waitcnt lgkmcnt(0)
	v_add_f32_e32 v0, v0, v32
	ds_bpermute_b32 v32, v24, v0
	s_waitcnt lgkmcnt(0)
	v_add_f32_e32 v0, v0, v32
	ds_bpermute_b32 v32, v25, v0
	s_waitcnt lgkmcnt(0)
	v_add_f32_e32 v0, v0, v32
	ds_bpermute_b32 v28, v26, v0
	s_and_saveexec_b64 s[2:3], vcc
	s_cbranch_execz .LBB0_431
	s_waitcnt lgkmcnt(0)
	v_add_f32_e32 v0, v0, v28
	global_atomic_add_f32 v[20:21], v0, off offset:-64
.LBB0_431:
	s_or_b64 exec, exec, s[2:3]
	v_lshl_add_u64 v[36:37], v[16:17], 0, s[0:1]
	s_waitcnt lgkmcnt(0)
	ds_read_b128 v[32:35], v27 offset:4224
	s_waitcnt vmcnt(4) lgkmcnt(0)
	v_pk_fma_f32 v[32:33], v[32:33], 0.5, v[44:45] op_sel_hi:[1,0,1]
	s_nop 0
	v_mul_f32_e32 v0, v33, v33
	v_pk_fma_f32 v[34:35], v[34:35], 0.5, v[46:47] op_sel_hi:[1,0,1]
	v_fmac_f32_e32 v0, v32, v32
	v_fmac_f32_e32 v0, v34, v34
	v_fmac_f32_e32 v0, v35, v35
	ds_bpermute_b32 v28, v22, v0
	global_store_dwordx4 v[36:37], v[32:35], off
	v_cvt_pk_bf16_f32 v30, v32, v33
	v_cvt_pk_bf16_f32 v31, v34, v35
	v_lshl_add_u64 v[32:33], s[94:95], 0, v[14:15]
	s_waitcnt lgkmcnt(0)
	v_add_f32_e32 v0, v0, v28
	ds_bpermute_b32 v28, v23, v0
	global_store_dwordx2 v[32:33], v[30:31], off
	s_waitcnt lgkmcnt(0)
	v_add_f32_e32 v0, v0, v28
	ds_bpermute_b32 v28, v24, v0
	s_waitcnt lgkmcnt(0)
	v_add_f32_e32 v0, v0, v28
	ds_bpermute_b32 v28, v25, v0
	s_waitcnt lgkmcnt(0)
	v_add_f32_e32 v0, v0, v28
	ds_bpermute_b32 v28, v26, v0
	s_and_saveexec_b64 s[2:3], vcc
	s_cbranch_execz .LBB0_433
	s_waitcnt lgkmcnt(0)
	v_add_f32_e32 v0, v0, v28
	global_atomic_add_f32 v[20:21], v0, off offset:-32
.LBB0_433:
	s_or_b64 exec, exec, s[2:3]
	v_lshl_add_u64 v[36:37], v[10:11], 0, s[0:1]
	s_waitcnt lgkmcnt(0)
	ds_read_b128 v[32:35], v27 offset:8448
	s_waitcnt vmcnt(5) lgkmcnt(0)
	v_pk_fma_f32 v[32:33], v[32:33], 0.5, v[48:49] op_sel_hi:[1,0,1]
	s_nop 0
	v_mul_f32_e32 v0, v33, v33
	v_pk_fma_f32 v[34:35], v[34:35], 0.5, v[50:51] op_sel_hi:[1,0,1]
	v_fmac_f32_e32 v0, v32, v32
	v_fmac_f32_e32 v0, v34, v34
	v_fmac_f32_e32 v0, v35, v35
	ds_bpermute_b32 v28, v22, v0
	global_store_dwordx4 v[36:37], v[32:35], off
	v_cvt_pk_bf16_f32 v30, v32, v33
	v_cvt_pk_bf16_f32 v31, v34, v35
	v_lshl_add_u64 v[32:33], s[94:95], 0, v[8:9]
	s_waitcnt lgkmcnt(0)
	v_add_f32_e32 v0, v0, v28
	ds_bpermute_b32 v28, v23, v0
	global_store_dwordx2 v[32:33], v[30:31], off
	s_waitcnt lgkmcnt(0)
	v_add_f32_e32 v0, v0, v28
	ds_bpermute_b32 v28, v24, v0
	s_waitcnt lgkmcnt(0)
	v_add_f32_e32 v0, v0, v28
	ds_bpermute_b32 v28, v25, v0
	s_waitcnt lgkmcnt(0)
	v_add_f32_e32 v0, v0, v28
	ds_bpermute_b32 v28, v26, v0
	s_and_saveexec_b64 s[2:3], vcc
	s_cbranch_execz .LBB0_435
	s_waitcnt lgkmcnt(0)
	v_add_f32_e32 v0, v0, v28
	global_atomic_add_f32 v[20:21], v0, off
.LBB0_435:
	s_or_b64 exec, exec, s[2:3]
	v_lshl_add_u64 v[36:37], v[4:5], 0, s[0:1]
	s_waitcnt lgkmcnt(0)
	ds_read_b128 v[32:35], v27 offset:12672
	s_waitcnt vmcnt(6) lgkmcnt(0)
	v_pk_fma_f32 v[32:33], v[32:33], 0.5, v[52:53] op_sel_hi:[1,0,1]
	s_nop 0
	v_mul_f32_e32 v0, v33, v33
	v_pk_fma_f32 v[34:35], v[34:35], 0.5, v[54:55] op_sel_hi:[1,0,1]
	v_fmac_f32_e32 v0, v32, v32
	v_fmac_f32_e32 v0, v34, v34
	v_fmac_f32_e32 v0, v35, v35
	ds_bpermute_b32 v28, v22, v0
	global_store_dwordx4 v[36:37], v[32:35], off
	v_cvt_pk_bf16_f32 v30, v32, v33
	v_cvt_pk_bf16_f32 v31, v34, v35
	v_lshl_add_u64 v[32:33], s[94:95], 0, v[2:3]
	s_waitcnt lgkmcnt(0)
	v_add_f32_e32 v0, v0, v28
	ds_bpermute_b32 v28, v23, v0
	global_store_dwordx2 v[32:33], v[30:31], off
	s_waitcnt lgkmcnt(0)
	v_add_f32_e32 v0, v0, v28
	ds_bpermute_b32 v28, v24, v0
	s_waitcnt lgkmcnt(0)
	v_add_f32_e32 v0, v0, v28
	ds_bpermute_b32 v28, v25, v0
	s_waitcnt lgkmcnt(0)
	v_add_f32_e32 v0, v0, v28
	ds_bpermute_b32 v28, v26, v0
	s_and_saveexec_b64 s[2:3], vcc
	s_cbranch_execz .LBB0_428
	s_waitcnt lgkmcnt(0)
	v_add_f32_e32 v0, v0, v28
	global_atomic_add_f32 v[20:21], v0, off offset:32
	s_branch .LBB0_428

; DI unsigned pk2(float a, float b) { f32x2 v = {a, b}; bf16x2_t r = __builtin_convertvector(v, bf16x2_t); return __builtin_bit_cast(unsigned, r); }
; template <int NJ> DI void resid_epilogue(float* __restrict__ x, bf16_t* __restrict__ xb, float* __restrict__ ssn, int mt, int nt, const float* cl, float scale) {
;     ...
; #pragma unroll 4
;   for (int it = 0; it < NP; ++it) {
;     const int row = r0 + RPP * it;
;     const f32x4 c = *(const f32x4*)(cl + row * CLD + c4);
;     const size_t gi = (size_t)(mt * 128 + row) * DM + nt * (64 * NJ) + c4;
;     f32x4 xv = *(const f32x4*)(x + gi);
;     xv = xv + scale * c;
;     *(f32x4*)(x + gi) = xv;
;     u32x2 p; p.x = pk2(xv[0], xv[1]); p.y = pk2(xv[2], xv[3]);
;     *(u32x2*)(xb + (size_t)(mt * 128 + row) * LDX + nt * (64 * NJ) + c4) = p;
;     float s_ = xv[0] * xv[0] + xv[1] * xv[1] + xv[2] * xv[2] + xv[3] * xv[3];
;     if (NJ == 2) s_ += __shfl_xor(s_, 16);
;     s_ += __shfl_xor(s_, 8); s_ += __shfl_xor(s_, 4); s_ += __shfl_xor(s_, 2); s_ += __shfl_xor(s_, 1);
;     if ((tid & (LPR - 1)) == 0) atomicAdd(ssn + mt * 128 + row, s_);
;   }
.LBB0_1027:
	v_lshl_add_u64 v[20:21], v[6:7], 0, s[0:1]
	s_waitcnt lgkmcnt(0)
	global_load_dwordx4 v[28:31], v[20:21], off
	v_lshl_add_u64 v[38:39], v[16:17], 0, s[0:1]
	global_load_dwordx4 v[44:47], v[38:39], off
	v_lshl_add_u64 v[40:41], v[10:11], 0, s[0:1]
	global_load_dwordx4 v[48:51], v[40:41], off
	v_lshl_add_u64 v[42:43], v[4:5], 0, s[0:1]
	global_load_dwordx4 v[52:55], v[42:43], off
	ds_read_b128 v[32:35], v27
	s_waitcnt vmcnt(3) lgkmcnt(0)
	v_pk_add_f32 v[28:29], v[32:33], v[28:29]
	s_nop 0
	v_mul_f32_e32 v0, v29, v29
	v_pk_add_f32 v[30:31], v[34:35], v[30:31]
	v_fmac_f32_e32 v0, v28, v28
	v_fmac_f32_e32 v0, v30, v30
	v_fmac_f32_e32 v0, v31, v31
	ds_bpermute_b32 v32, v22, v0
	global_store_dwordx4 v[20:21], v[28:31], off
	v_cvt_pk_bf16_f32 v20, v28, v29
	v_cvt_pk_bf16_f32 v21, v30, v31
	v_lshl_add_u64 v[30:31], s[94:95], 0, v[18:19]
	s_waitcnt lgkmcnt(0)
	v_add_f32_e32 v0, v0, v32
	ds_bpermute_b32 v32, v23, v0
	global_store_dwordx2 v[30:31], v[20:21], off
	v_lshl_add_u64 v[20:21], s[94:95], 0, v[12:13]
	s_waitcnt lgkmcnt(0)
	v_add_f32_e32 v0, v0, v32
	ds_bpermute_b32 v32, v24, v0
	s_waitcnt lgkmcnt(0)
	v_add_f32_e32 v0, v0, v32
	ds_bpermute_b32 v32, v25, v0
	s_waitcnt lgkmcnt(0)
	v_add_f32_e32 v0, v0, v32
	ds_bpermute_b32 v28, v26, v0
	s_and_saveexec_b64 s[2:3], vcc
	s_cbranch_execz .LBB0_1029
	s_waitcnt lgkmcnt(0)
	v_add_f32_e32 v0, v0, v28
	global_atomic_add_f32 v[20:21], v0, off offset:-64
.LBB0_1029:
	s_or_b64 exec, exec, s[2:3]
	v_lshl_add_u64 v[36:37], v[16:17], 0, s[0:1]
	s_waitcnt lgkmcnt(0)
	ds_read_b128 v[32:35], v27 offset:4224
	s_waitcnt vmcnt(4) lgkmcnt(0)
	v_pk_add_f32 v[32:33], v[32:33], v[44:45]
	s_nop 0
	v_mul_f32_e32 v0, v33, v33
	v_pk_add_f32 v[34:35], v[34:35], v[46:47]
	v_fmac_f32_e32 v0, v32, v32
	v_fmac_f32_e32 v0, v34, v34
	v_fmac_f32_e32 v0, v35, v35
	ds_bpermute_b32 v28, v22, v0
	global_store_dwordx4 v[36:37], v[32:35], off
	v_cvt_pk_bf16_f32 v30, v32, v33
	v_cvt_pk_bf16_f32 v31, v34, v35
	v_lshl_add_u64 v[32:33], s[94:95], 0, v[14:15]
	s_waitcnt lgkmcnt(0)
	v_add_f32_e32 v0, v0, v28
	ds_bpermute_b32 v28, v23, v0
	global_store_dwordx2 v[32:33], v[30:31], off
	s_waitcnt lgkmcnt(0)
	v_add_f32_e32 v0, v0, v28
	ds_bpermute_b32 v28, v24, v0
	s_waitcnt lgkmcnt(0)
	v_add_f32_e32 v0, v0, v28
	ds_bpermute_b32 v28, v25, v0
	s_waitcnt lgkmcnt(0)
	v_add_f32_e32 v0, v0, v28
	ds_bpermute_b32 v28, v26, v0
	s_and_saveexec_b64 s[2:3], vcc
	s_cbranch_execz .LBB0_1031
	s_waitcnt lgkmcnt(0)
	v_add_f32_e32 v0, v0, v28
	global_atomic_add_f32 v[20:21], v0, off offset:-32
.LBB0_1031:
	s_or_b64 exec, exec, s[2:3]
	v_lshl_add_u64 v[36:37], v[10:11], 0, s[0:1]
	s_waitcnt lgkmcnt(0)
	ds_read_b128 v[32:35], v27 offset:8448
	s_waitcnt vmcnt(5) lgkmcnt(0)
	v_pk_add_f32 v[32:33], v[32:33], v[48:49]
	s_nop 0
	v_mul_f32_e32 v0, v33, v33
	v_pk_add_f32 v[34:35], v[34:35], v[50:51]
	v_fmac_f32_e32 v0, v32, v32
	v_fmac_f32_e32 v0, v34, v34
	v_fmac_f32_e32 v0, v35, v35
	ds_bpermute_b32 v28, v22, v0
	global_store_dwordx4 v[36:37], v[32:35], off
	v_cvt_pk_bf16_f32 v30, v32, v33
	v_cvt_pk_bf16_f32 v31, v34, v35
	v_lshl_add_u64 v[32:33], s[94:95], 0, v[8:9]
	s_waitcnt lgkmcnt(0)
	v_add_f32_e32 v0, v0, v28
	ds_bpermute_b32 v28, v23, v0
	global_store_dwordx2 v[32:33], v[30:31], off
	s_waitcnt lgkmcnt(0)
	v_add_f32_e32 v0, v0, v28
	ds_bpermute_b32 v28, v24, v0
	s_waitcnt lgkmcnt(0)
	v_add_f32_e32 v0, v0, v28
	ds_bpermute_b32 v28, v25, v0
	s_waitcnt lgkmcnt(0)
	v_add_f32_e32 v0, v0, v28
	ds_bpermute_b32 v28, v26, v0
	s_and_saveexec_b64 s[2:3], vcc
	s_cbranch_execz .LBB0_1033
	s_waitcnt lgkmcnt(0)
	v_add_f32_e32 v0, v0, v28
	global_atomic_add_f32 v[20:21], v0, off
.LBB0_1033:
	s_or_b64 exec, exec, s[2:3]
	v_lshl_add_u64 v[36:37], v[4:5], 0, s[0:1]
	s_waitcnt lgkmcnt(0)
	ds_read_b128 v[32:35], v27 offset:12672
	s_waitcnt vmcnt(6) lgkmcnt(0)
	v_pk_add_f32 v[32:33], v[32:33], v[52:53]
	s_nop 0
	v_mul_f32_e32 v0, v33, v33
	v_pk_add_f32 v[34:35], v[34:35], v[54:55]
	v_fmac_f32_e32 v0, v32, v32
	v_fmac_f32_e32 v0, v34, v34
	v_fmac_f32_e32 v0, v35, v35
	ds_bpermute_b32 v28, v22, v0
	global_store_dwordx4 v[36:37], v[32:35], off
	v_cvt_pk_bf16_f32 v30, v32, v33
	v_cvt_pk_bf16_f32 v31, v34, v35
	v_lshl_add_u64 v[32:33], s[94:95], 0, v[2:3]
	s_waitcnt lgkmcnt(0)
	v_add_f32_e32 v0, v0, v28
	ds_bpermute_b32 v28, v23, v0
	global_store_dwordx2 v[32:33], v[30:31], off
	s_waitcnt lgkmcnt(0)
	v_add_f32_e32 v0, v0, v28
	ds_bpermute_b32 v28, v24, v0
	s_waitcnt lgkmcnt(0)
	v_add_f32_e32 v0, v0, v28
	ds_bpermute_b32 v28, v25, v0
	s_waitcnt lgkmcnt(0)
	v_add_f32_e32 v0, v0, v28
	ds_bpermute_b32 v28, v26, v0
	s_and_saveexec_b64 s[2:3], vcc
	s_cbranch_execz .LBB0_1026
	s_waitcnt lgkmcnt(0)
	v_add_f32_e32 v0, v0, v28
	global_atomic_add_f32 v[20:21], v0, off offset:32
	s_branch .LBB0_1026

; DI unsigned pk2(float a, float b) { f32x2 v = {a, b}; bf16x2_t r = __builtin_convertvector(v, bf16x2_t); return __builtin_bit_cast(unsigned, r); }
; template <int NJ> DI void resid_epilogue(float* __restrict__ x, bf16_t* __restrict__ xb, float* __restrict__ ssn, int mt, int nt, const float* cl, float scale) {
;     ...
; #pragma unroll 4
;   for (int it = 0; it < NP; ++it) {
;     const int row = r0 + RPP * it;
;     const f32x4 c = *(const f32x4*)(cl + row * CLD + c4);
;     const size_t gi = (size_t)(mt * 128 + row) * DM + nt * (64 * NJ) + c4;
;     f32x4 xv = *(const f32x4*)(x + gi);
;     xv = xv + scale * c;
;     *(f32x4*)(x + gi) = xv;
;     u32x2 p; p.x = pk2(xv[0], xv[1]); p.y = pk2(xv[2], xv[3]);
;     *(u32x2*)(xb + (size_t)(mt * 128 + row) * LDX + nt * (64 * NJ) + c4) = p;
;     float s_ = xv[0] * xv[0] + xv[1] * xv[1] + xv[2] * xv[2] + xv[3] * xv[3];
;     if (NJ == 2) s_ += __shfl_xor(s_, 16);
;     s_ += __shfl_xor(s_, 8); s_ += __shfl_xor(s_, 4); s_ += __shfl_xor(s_, 2); s_ += __shfl_xor(s_, 1);
;     if ((tid & (LPR - 1)) == 0) atomicAdd(ssn + mt * 128 + row, s_);
;   }
.LBB0_1228:
	v_lshl_add_u64 v[20:21], v[6:7], 0, s[0:1]
	s_waitcnt lgkmcnt(0)
	global_load_dwordx4 v[28:31], v[20:21], off
	v_lshl_add_u64 v[38:39], v[16:17], 0, s[0:1]
	global_load_dwordx4 v[44:47], v[38:39], off
	v_lshl_add_u64 v[40:41], v[10:11], 0, s[0:1]
	global_load_dwordx4 v[48:51], v[40:41], off
	v_lshl_add_u64 v[42:43], v[4:5], 0, s[0:1]
	global_load_dwordx4 v[52:55], v[42:43], off
	ds_read_b128 v[32:35], v27
	s_waitcnt vmcnt(3) lgkmcnt(0)
	v_pk_add_f32 v[28:29], v[32:33], v[28:29]
	s_nop 0
	v_mul_f32_e32 v0, v29, v29
	v_pk_add_f32 v[30:31], v[34:35], v[30:31]
	v_fmac_f32_e32 v0, v28, v28
	v_fmac_f32_e32 v0, v30, v30
	v_fmac_f32_e32 v0, v31, v31
	ds_bpermute_b32 v32, v22, v0
	global_store_dwordx4 v[20:21], v[28:31], off
	v_cvt_pk_bf16_f32 v20, v28, v29
	v_cvt_pk_bf16_f32 v21, v30, v31
	v_lshl_add_u64 v[30:31], s[94:95], 0, v[18:19]
	s_waitcnt lgkmcnt(0)
	v_add_f32_e32 v0, v0, v32
	ds_bpermute_b32 v32, v23, v0
	global_store_dwordx2 v[30:31], v[20:21], off
	v_lshl_add_u64 v[20:21], s[94:95], 0, v[12:13]
	s_waitcnt lgkmcnt(0)
	v_add_f32_e32 v0, v0, v32
	ds_bpermute_b32 v32, v24, v0
	s_waitcnt lgkmcnt(0)
	v_add_f32_e32 v0, v0, v32
	ds_bpermute_b32 v32, v25, v0
	s_waitcnt lgkmcnt(0)
	v_add_f32_e32 v0, v0, v32
	ds_bpermute_b32 v28, v26, v0
	s_and_saveexec_b64 s[2:3], s[36:37]
	s_cbranch_execz .LBB0_1230
	s_waitcnt lgkmcnt(0)
	v_add_f32_e32 v0, v0, v28
	global_atomic_add_f32 v[20:21], v0, off offset:-64
.LBB0_1230:
	s_or_b64 exec, exec, s[2:3]
	v_lshl_add_u64 v[36:37], v[16:17], 0, s[0:1]
	s_waitcnt lgkmcnt(0)
	ds_read_b128 v[32:35], v27 offset:4224
	s_waitcnt vmcnt(4) lgkmcnt(0)
	v_pk_add_f32 v[32:33], v[32:33], v[44:45]
	s_nop 0
	v_mul_f32_e32 v0, v33, v33
	v_pk_add_f32 v[34:35], v[34:35], v[46:47]
	v_fmac_f32_e32 v0, v32, v32
	v_fmac_f32_e32 v0, v34, v34
	v_fmac_f32_e32 v0, v35, v35
	ds_bpermute_b32 v28, v22, v0
	global_store_dwordx4 v[36:37], v[32:35], off
	v_cvt_pk_bf16_f32 v30, v32, v33
	v_cvt_pk_bf16_f32 v31, v34, v35
	v_lshl_add_u64 v[32:33], s[94:95], 0, v[14:15]
	s_waitcnt lgkmcnt(0)
	v_add_f32_e32 v0, v0, v28
	ds_bpermute_b32 v28, v23, v0
	global_store_dwordx2 v[32:33], v[30:31], off
	s_waitcnt lgkmcnt(0)
	v_add_f32_e32 v0, v0, v28
	ds_bpermute_b32 v28, v24, v0
	s_waitcnt lgkmcnt(0)
	v_add_f32_e32 v0, v0, v28
	ds_bpermute_b32 v28, v25, v0
	s_waitcnt lgkmcnt(0)
	v_add_f32_e32 v0, v0, v28
	ds_bpermute_b32 v28, v26, v0
	s_and_saveexec_b64 s[2:3], s[36:37]
	s_cbranch_execz .LBB0_1232
	s_waitcnt lgkmcnt(0)
	v_add_f32_e32 v0, v0, v28
	global_atomic_add_f32 v[20:21], v0, off offset:-32
.LBB0_1232:
	s_or_b64 exec, exec, s[2:3]
	v_lshl_add_u64 v[36:37], v[10:11], 0, s[0:1]
	s_waitcnt lgkmcnt(0)
	ds_read_b128 v[32:35], v27 offset:8448
	s_waitcnt vmcnt(5) lgkmcnt(0)
	v_pk_add_f32 v[32:33], v[32:33], v[48:49]
	s_nop 0
	v_mul_f32_e32 v0, v33, v33
	v_pk_add_f32 v[34:35], v[34:35], v[50:51]
	v_fmac_f32_e32 v0, v32, v32
	v_fmac_f32_e32 v0, v34, v34
	v_fmac_f32_e32 v0, v35, v35
	ds_bpermute_b32 v28, v22, v0
	global_store_dwordx4 v[36:37], v[32:35], off
	v_cvt_pk_bf16_f32 v30, v32, v33
	v_cvt_pk_bf16_f32 v31, v34, v35
	v_lshl_add_u64 v[32:33], s[94:95], 0, v[8:9]
	s_waitcnt lgkmcnt(0)
	v_add_f32_e32 v0, v0, v28
	ds_bpermute_b32 v28, v23, v0
	global_store_dwordx2 v[32:33], v[30:31], off
	s_waitcnt lgkmcnt(0)
	v_add_f32_e32 v0, v0, v28
	ds_bpermute_b32 v28, v24, v0
	s_waitcnt lgkmcnt(0)
	v_add_f32_e32 v0, v0, v28
	ds_bpermute_b32 v28, v25, v0
	s_waitcnt lgkmcnt(0)
	v_add_f32_e32 v0, v0, v28
	ds_bpermute_b32 v28, v26, v0
	s_and_saveexec_b64 s[2:3], s[36:37]
	s_cbranch_execz .LBB0_1234
	s_waitcnt lgkmcnt(0)
	v_add_f32_e32 v0, v0, v28
	global_atomic_add_f32 v[20:21], v0, off
.LBB0_1234:
	s_or_b64 exec, exec, s[2:3]
	v_lshl_add_u64 v[36:37], v[4:5], 0, s[0:1]
	s_waitcnt lgkmcnt(0)
	ds_read_b128 v[32:35], v27 offset:12672
	s_waitcnt vmcnt(6) lgkmcnt(0)
	v_pk_add_f32 v[32:33], v[32:33], v[52:53]
	s_nop 0
	v_mul_f32_e32 v0, v33, v33
	v_pk_add_f32 v[34:35], v[34:35], v[54:55]
	v_fmac_f32_e32 v0, v32, v32
	v_fmac_f32_e32 v0, v34, v34
	v_fmac_f32_e32 v0, v35, v35
	ds_bpermute_b32 v28, v22, v0
	global_store_dwordx4 v[36:37], v[32:35], off
	v_cvt_pk_bf16_f32 v30, v32, v33
	v_cvt_pk_bf16_f32 v31, v34, v35
	v_lshl_add_u64 v[32:33], s[94:95], 0, v[2:3]
	s_waitcnt lgkmcnt(0)
	v_add_f32_e32 v0, v0, v28
	ds_bpermute_b32 v28, v23, v0
	global_store_dwordx2 v[32:33], v[30:31], off
	s_waitcnt lgkmcnt(0)
	v_add_f32_e32 v0, v0, v28
	ds_bpermute_b32 v28, v24, v0
	s_waitcnt lgkmcnt(0)
	v_add_f32_e32 v0, v0, v28
	ds_bpermute_b32 v28, v25, v0
	s_waitcnt lgkmcnt(0)
	v_add_f32_e32 v0, v0, v28
	ds_bpermute_b32 v28, v26, v0
	s_and_saveexec_b64 s[2:3], s[36:37]
	s_cbranch_execz .LBB0_1227
	s_waitcnt lgkmcnt(0)
	v_add_f32_e32 v0, v0, v28
	global_atomic_add_f32 v[20:21], v0, off offset:32
	s_branch .LBB0_1227
